# robustness: last-layer resid pass writes the second half-row's results into the row set's own consumed registers, so f32 store data are not rewritten for a whole row; plus the store->s_waitcnt pads
# baseline (speedup 1.0000x reference)
; __device__ __forceinline__ float bflo(unsigned w) { return __uint_as_float(w << 16); }
; __device__ __forceinline__ float bfhi(unsigned w) { return __uint_as_float(w & 0xffff0000u); }
; __device__ __forceinline__ void resid_rows(bf16_t* R, const bf16_t* Y, const float* ssqY, const float* g, float* rstd_out, float* outf, bool wf32, int row_lo, int row_hi, int yoff, int gw, int NGW, int lane) {
;     constexpr int RP = 4;
;     f32x4 gv[2][2];
; #pragma unroll
;     for (int j = 0; j < 2; ++j) { gv[j][0] = *(const f32x4*)(g + 8 * lane + 512 * j); gv[j][1] = *(const f32x4*)(g + 8 * lane + 512 * j + 4); }
;     for (int row0 = row_lo + gw; row0 < row_hi; row0 += RP * NGW) {
;         u32x4 rr[RP][2], oo[RP][2]; float ssv[RP];
; #pragma unroll
;         for (int k = 0; k < RP; ++k) { const int row = row0 + k * NGW; const bool ok = row < row_hi; const int rw = ok ? row : row0;
;             ssv[k] = ssqY[rw];
; #pragma unroll
;             for (int j = 0; j < 2; ++j) { const int c = 8 * lane + 512 * j; rr[k][j] = *(const u32x4*)(R + (size_t)rw * DM + c); oo[k][j] = *(const u32x4*)(Y + (size_t)(rw - yoff) * DM + c); } }
; #pragma unroll
;         for (int k = 0; k < RP; ++k) { const int row = row0 + k * NGW; if (row < row_hi) {
;             const float rs = __builtin_amdgcn_rsqf(ssv[k] * (1.0f / DM) + RMS_EPS); float s = 0.f;
; #pragma unroll
;             for (int j = 0; j < 2; ++j) { const int c = 8 * lane + 512 * j; const u32x4 r = rr[k][j], o = oo[k][j]; const f32x4 ga = gv[j][0], gb = gv[j][1];
;                 f32x4 ya, yb; ya[0] = bflo(r.x) + bflo(o.x) * rs * ga[0]; ya[1] = bfhi(r.x) + bfhi(o.x) * rs * ga[1]; ya[2] = bflo(r.y) + bflo(o.y) * rs * ga[2]; ya[3] = bfhi(r.y) + bfhi(o.y) * rs * ga[3];
;                 yb[0] = bflo(r.z) + bflo(o.z) * rs * gb[0]; yb[1] = bfhi(r.z) + bfhi(o.z) * rs * gb[1]; yb[2] = bflo(r.w) + bflo(o.w) * rs * gb[2]; yb[3] = bfhi(r.w) + bfhi(o.w) * rs * gb[3];
;                 if (wf32) { *(f32x4*)(outf + (size_t)row * DM + c) = ya; *(f32x4*)(outf + (size_t)row * DM + c + 4) = yb; }
;                 s += (ya[0] * ya[0] + ya[1] * ya[1]) + (ya[2] * ya[2] + ya[3] * ya[3]) + (yb[0] * yb[0] + yb[1] * yb[1]) + (yb[2] * yb[2] + yb[3] * yb[3]);
;                 u32x4 w; w.x = pk2(ya[0], ya[1]); w.y = pk2(ya[2], ya[3]); w.z = pk2(yb[0], yb[1]); w.w = pk2(yb[2], yb[3]); *(u32x4*)(R + (size_t)row * DM + c) = w; }
.Lrs2_last1:
	v_lshrrev_b32_e32 v114, 6, v0
	v_readlane_b32 s12, v255, 49
	v_readlane_b32 s13, v255, 4
	v_readfirstlane_b32 s18, v114
	s_load_dwordx2 s[4:5], s[0:1], 0x98
	s_load_dwordx2 s[10:11], s[0:1], 0x68
	s_load_dwordx2 s[6:7], s[0:1], 0x90
	s_add_i32 s13, s13, s18
	v_and_b32_e32 v115, 63, v0
	v_lshlrev_b32_e32 v114, 4, v115
	v_lshlrev_b32_e32 v115, 5, v115
	s_lshl_b32 s18, s12, 12
	s_lshl_b32 s19, s12, 18
	s_bfm_b64 s[8:9], 1, 63
	s_waitcnt lgkmcnt(0)
	s_add_u32 s10, s10, s18
	s_addc_u32 s11, s11, 0
	global_load_dwordx4 v[2:5], v115, s[10:11] offset:2048
	global_load_dwordx4 v[6:9], v115, s[10:11] offset:2064
	global_load_dwordx4 v[10:13], v115, s[10:11]
	global_load_dwordx4 v[14:17], v115, s[10:11] offset:16
	s_lshl_b32 s18, s13, 11
	v_add_u32_e32 v18, s18, v114
	v_mov_b32_e32 v19, v18
	v_mov_b32_e32 v20, v18
	s_lshl_b32 s18, s13, 2
	v_mov_b32_e32 v22, s18
	s_add_i32 s18, s18, s19
	v_mov_b32_e32 v21, s18
	s_lshl_b32 s18, s13, 12
	v_add_u32_e32 v23, s18, v115
	v_add_u32_e32 v18, 0x5001000, v18
	s_lshl_b32 s18, s13, 11
	v_add_u32_e32 v18, s18, v18
	s_lshl_b32 s18, s13, 11
	v_add_u32_e32 v20, s18, v20
	v_add_u32_e32 v21, 0x2d70000, v21
	s_lshl_b32 s18, s13, 2
	v_add_u32_e32 v21, s18, v21
	global_load_dwordx4 v[24:27], v18, s[4:5]
	global_load_dwordx4 v[32:35], v20, s[6:7]
	global_load_dwordx4 v[28:31], v18, s[4:5] offset:1024
	global_load_dwordx4 v[36:39], v20, s[6:7] offset:1024
	global_load_dword v40, v21, s[4:5]
	v_add_u32_e32 v18, 0x800, v18
	v_add_u32_e32 v20, 0x800, v20
	v_add_u32_e32 v21, 0x4, v21
	global_load_dwordx4 v[42:45], v18, s[4:5]
	global_load_dwordx4 v[50:53], v20, s[6:7]
	global_load_dwordx4 v[46:49], v18, s[4:5] offset:1024
	global_load_dwordx4 v[54:57], v20, s[6:7] offset:1024
	global_load_dword v58, v21, s[4:5]
	v_add_u32_e32 v18, 0x7ff800, v18
	v_add_u32_e32 v20, 0x7ff800, v20
	v_add_u32_e32 v21, 0x3ffc, v21
	global_load_dwordx4 v[60:63], v18, s[4:5]
	global_load_dwordx4 v[68:71], v20, s[6:7]
	global_load_dwordx4 v[64:67], v18, s[4:5] offset:1024
	global_load_dwordx4 v[72:75], v20, s[6:7] offset:1024
	global_load_dword v76, v21, s[4:5]
	v_add_u32_e32 v18, 0x800, v18
	v_add_u32_e32 v20, 0x800, v20
	v_add_u32_e32 v21, 0x4, v21
	global_load_dwordx4 v[78:81], v18, s[4:5]
	global_load_dwordx4 v[86:89], v20, s[6:7]
	global_load_dwordx4 v[82:85], v18, s[4:5] offset:1024
	global_load_dwordx4 v[90:93], v20, s[6:7] offset:1024
	global_load_dword v94, v21, s[4:5]
	s_waitcnt vmcnt(15)
	v_fmamk_f32 v96, v40, 0x3a800000, v244
	v_rsq_f32_e32 v96, v96
	v_add_u32_e32 v23, 0x4000000, v23
	s_lshl_b32 s18, s13, 12
	v_add_u32_e32 v23, s18, v23
	v_lshlrev_b32_e32 v106, 16, v32
	v_and_b32_e32 v107, 0xffff0000, v32
	v_lshlrev_b32_e32 v108, 16, v24
	v_and_b32_e32 v109, 0xffff0000, v24
	v_pk_mul_f32 v[106:107], v[96:97], v[106:107] op_sel_hi:[0,1]
	v_pk_fma_f32 v[98:99], v[10:11], v[106:107], v[108:109]
	v_lshlrev_b32_e32 v106, 16, v33
	v_and_b32_e32 v107, 0xffff0000, v33
	v_lshlrev_b32_e32 v108, 16, v25
	v_and_b32_e32 v109, 0xffff0000, v25
	v_pk_mul_f32 v[106:107], v[96:97], v[106:107] op_sel_hi:[0,1]
	v_pk_fma_f32 v[100:101], v[12:13], v[106:107], v[108:109]
	v_lshlrev_b32_e32 v106, 16, v34
	v_and_b32_e32 v107, 0xffff0000, v34
	v_lshlrev_b32_e32 v108, 16, v26
	v_and_b32_e32 v109, 0xffff0000, v26
	v_pk_mul_f32 v[106:107], v[96:97], v[106:107] op_sel_hi:[0,1]
	v_pk_fma_f32 v[102:103], v[14:15], v[106:107], v[108:109]
	v_lshlrev_b32_e32 v106, 16, v35
	v_and_b32_e32 v107, 0xffff0000, v35
	v_lshlrev_b32_e32 v108, 16, v27
	v_and_b32_e32 v109, 0xffff0000, v27
	v_pk_mul_f32 v[106:107], v[96:97], v[106:107] op_sel_hi:[0,1]
	v_pk_fma_f32 v[104:105], v[16:17], v[106:107], v[108:109]
	global_store_dwordx4 v23, v[98:101], s[6:7]
	global_store_dwordx4 v23, v[102:105], s[6:7] offset:16
	v_lshlrev_b32_e32 v106, 16, v36
	v_and_b32_e32 v107, 0xffff0000, v36
	v_lshlrev_b32_e32 v108, 16, v28
	v_and_b32_e32 v109, 0xffff0000, v28
	v_pk_mul_f32 v[106:107], v[96:97], v[106:107] op_sel_hi:[0,1]
	v_pk_fma_f32 v[24:25], v[2:3], v[106:107], v[108:109]
	v_lshlrev_b32_e32 v106, 16, v37
	v_and_b32_e32 v107, 0xffff0000, v37
	v_lshlrev_b32_e32 v108, 16, v29
	v_and_b32_e32 v109, 0xffff0000, v29
	v_pk_mul_f32 v[106:107], v[96:97], v[106:107] op_sel_hi:[0,1]
	v_pk_fma_f32 v[26:27], v[4:5], v[106:107], v[108:109]
	v_lshlrev_b32_e32 v106, 16, v38
	v_and_b32_e32 v107, 0xffff0000, v38
	v_lshlrev_b32_e32 v108, 16, v30
	v_and_b32_e32 v109, 0xffff0000, v30
	v_pk_mul_f32 v[106:107], v[96:97], v[106:107] op_sel_hi:[0,1]
	v_pk_fma_f32 v[32:33], v[6:7], v[106:107], v[108:109]
	v_lshlrev_b32_e32 v106, 16, v39
	v_and_b32_e32 v107, 0xffff0000, v39
	v_lshlrev_b32_e32 v108, 16, v31
	v_and_b32_e32 v109, 0xffff0000, v31
	v_pk_mul_f32 v[106:107], v[96:97], v[106:107] op_sel_hi:[0,1]
	v_pk_fma_f32 v[34:35], v[8:9], v[106:107], v[108:109]
	global_store_dwordx4 v23, v[24:27], s[6:7] offset:2048
	global_store_dwordx4 v23, v[32:35], s[6:7] offset:2064
	v_add_u32_e32 v18, 0x7ff800, v18
	v_add_u32_e32 v20, 0x7ff800, v20
	v_add_u32_e32 v21, 0x3ffc, v21
	global_load_dwordx4 v[24:27], v18, s[4:5]
	global_load_dwordx4 v[32:35], v20, s[6:7]
	global_load_dwordx4 v[28:31], v18, s[4:5] offset:1024
	global_load_dwordx4 v[36:39], v20, s[6:7] offset:1024
	global_load_dword v40, v21, s[4:5]
	s_waitcnt vmcnt(19)
; __device__ __forceinline__ float bflo(unsigned w) { return __uint_as_float(w << 16); }
; __device__ __forceinline__ float bfhi(unsigned w) { return __uint_as_float(w & 0xffff0000u); }
; __device__ __forceinline__ void resid_rows(bf16_t* R, const bf16_t* Y, const float* ssqY, const float* g, float* rstd_out, float* outf, bool wf32, int row_lo, int row_hi, int yoff, int gw, int NGW, int lane) {
;     ...
;         for (int k = 0; k < RP; ++k) { const int row = row0 + k * NGW; const bool ok = row < row_hi; const int rw = ok ? row : row0;
;             ssv[k] = ssqY[rw];
; #pragma unroll
;             for (int j = 0; j < 2; ++j) { const int c = 8 * lane + 512 * j; rr[k][j] = *(const u32x4*)(R + (size_t)rw * DM + c); oo[k][j] = *(const u32x4*)(Y + (size_t)(rw - yoff) * DM + c); } }
; #pragma unroll
;         for (int k = 0; k < RP; ++k) { const int row = row0 + k * NGW; if (row < row_hi) {
;             const float rs = __builtin_amdgcn_rsqf(ssv[k] * (1.0f / DM) + RMS_EPS); float s = 0.f;
; #pragma unroll
;             for (int j = 0; j < 2; ++j) { const int c = 8 * lane + 512 * j; const u32x4 r = rr[k][j], o = oo[k][j]; const f32x4 ga = gv[j][0], gb = gv[j][1];
;                 f32x4 ya, yb; ya[0] = bflo(r.x) + bflo(o.x) * rs * ga[0]; ya[1] = bfhi(r.x) + bfhi(o.x) * rs * ga[1]; ya[2] = bflo(r.y) + bflo(o.y) * rs * ga[2]; ya[3] = bfhi(r.y) + bfhi(o.y) * rs * ga[3];
;                 yb[0] = bflo(r.z) + bflo(o.z) * rs * gb[0]; yb[1] = bfhi(r.z) + bfhi(o.z) * rs * gb[1]; yb[2] = bflo(r.w) + bflo(o.w) * rs * gb[2]; yb[3] = bfhi(r.w) + bfhi(o.w) * rs * gb[3];
;                 if (wf32) { *(f32x4*)(outf + (size_t)row * DM + c) = ya; *(f32x4*)(outf + (size_t)row * DM + c + 4) = yb; }
;                 s += (ya[0] * ya[0] + ya[1] * ya[1]) + (ya[2] * ya[2] + ya[3] * ya[3]) + (yb[0] * yb[0] + yb[1] * yb[1]) + (yb[2] * yb[2] + yb[3] * yb[3]);
;                 u32x4 w; w.x = pk2(ya[0], ya[1]); w.y = pk2(ya[2], ya[3]); w.z = pk2(yb[0], yb[1]); w.w = pk2(yb[2], yb[3]); *(u32x4*)(R + (size_t)row * DM + c) = w; }
	v_fmamk_f32 v96, v58, 0x3a800000, v244
	v_rsq_f32_e32 v96, v96
	v_add_u32_e32 v23, 0x1000, v23
	v_lshlrev_b32_e32 v106, 16, v50
	v_and_b32_e32 v107, 0xffff0000, v50
	v_lshlrev_b32_e32 v108, 16, v42
	v_and_b32_e32 v109, 0xffff0000, v42
	v_pk_mul_f32 v[106:107], v[96:97], v[106:107] op_sel_hi:[0,1]
	v_pk_fma_f32 v[98:99], v[10:11], v[106:107], v[108:109]
	v_lshlrev_b32_e32 v106, 16, v51
	v_and_b32_e32 v107, 0xffff0000, v51
	v_lshlrev_b32_e32 v108, 16, v43
	v_and_b32_e32 v109, 0xffff0000, v43
	v_pk_mul_f32 v[106:107], v[96:97], v[106:107] op_sel_hi:[0,1]
	v_pk_fma_f32 v[100:101], v[12:13], v[106:107], v[108:109]
	v_lshlrev_b32_e32 v106, 16, v52
	v_and_b32_e32 v107, 0xffff0000, v52
	v_lshlrev_b32_e32 v108, 16, v44
	v_and_b32_e32 v109, 0xffff0000, v44
	v_pk_mul_f32 v[106:107], v[96:97], v[106:107] op_sel_hi:[0,1]
	v_pk_fma_f32 v[102:103], v[14:15], v[106:107], v[108:109]
	v_lshlrev_b32_e32 v106, 16, v53
	v_and_b32_e32 v107, 0xffff0000, v53
	v_lshlrev_b32_e32 v108, 16, v45
	v_and_b32_e32 v109, 0xffff0000, v45
	v_pk_mul_f32 v[106:107], v[96:97], v[106:107] op_sel_hi:[0,1]
	v_pk_fma_f32 v[104:105], v[16:17], v[106:107], v[108:109]
	global_store_dwordx4 v23, v[98:101], s[6:7]
	global_store_dwordx4 v23, v[102:105], s[6:7] offset:16
	v_lshlrev_b32_e32 v106, 16, v54
	v_and_b32_e32 v107, 0xffff0000, v54
	v_lshlrev_b32_e32 v108, 16, v46
	v_and_b32_e32 v109, 0xffff0000, v46
	v_pk_mul_f32 v[106:107], v[96:97], v[106:107] op_sel_hi:[0,1]
	v_pk_fma_f32 v[42:43], v[2:3], v[106:107], v[108:109]
	v_lshlrev_b32_e32 v106, 16, v55
	v_and_b32_e32 v107, 0xffff0000, v55
	v_lshlrev_b32_e32 v108, 16, v47
	v_and_b32_e32 v109, 0xffff0000, v47
	v_pk_mul_f32 v[106:107], v[96:97], v[106:107] op_sel_hi:[0,1]
	v_pk_fma_f32 v[44:45], v[4:5], v[106:107], v[108:109]
	v_lshlrev_b32_e32 v106, 16, v56
	v_and_b32_e32 v107, 0xffff0000, v56
	v_lshlrev_b32_e32 v108, 16, v48
	v_and_b32_e32 v109, 0xffff0000, v48
	v_pk_mul_f32 v[106:107], v[96:97], v[106:107] op_sel_hi:[0,1]
	v_pk_fma_f32 v[50:51], v[6:7], v[106:107], v[108:109]
	v_lshlrev_b32_e32 v106, 16, v57
	v_and_b32_e32 v107, 0xffff0000, v57
	v_lshlrev_b32_e32 v108, 16, v49
	v_and_b32_e32 v109, 0xffff0000, v49
	v_pk_mul_f32 v[106:107], v[96:97], v[106:107] op_sel_hi:[0,1]
	v_pk_fma_f32 v[52:53], v[8:9], v[106:107], v[108:109]
	global_store_dwordx4 v23, v[42:45], s[6:7] offset:2048
	global_store_dwordx4 v23, v[50:53], s[6:7] offset:2064
	v_add_u32_e32 v18, 0x800, v18
	v_add_u32_e32 v20, 0x800, v20
	v_add_u32_e32 v21, 0x4, v21
	global_load_dwordx4 v[42:45], v18, s[4:5]
	global_load_dwordx4 v[50:53], v20, s[6:7]
	global_load_dwordx4 v[46:49], v18, s[4:5] offset:1024
	global_load_dwordx4 v[54:57], v20, s[6:7] offset:1024
	global_load_dword v58, v21, s[4:5]
	s_waitcnt vmcnt(23)
	v_fmamk_f32 v96, v76, 0x3a800000, v244
	v_rsq_f32_e32 v96, v96
	v_add_u32_e32 v23, 0xfff000, v23
	v_lshlrev_b32_e32 v106, 16, v68
	v_and_b32_e32 v107, 0xffff0000, v68
	v_lshlrev_b32_e32 v108, 16, v60
	v_and_b32_e32 v109, 0xffff0000, v60
	v_pk_mul_f32 v[106:107], v[96:97], v[106:107] op_sel_hi:[0,1]
	v_pk_fma_f32 v[98:99], v[10:11], v[106:107], v[108:109]
	v_lshlrev_b32_e32 v106, 16, v69
	v_and_b32_e32 v107, 0xffff0000, v69
	v_lshlrev_b32_e32 v108, 16, v61
	v_and_b32_e32 v109, 0xffff0000, v61
	v_pk_mul_f32 v[106:107], v[96:97], v[106:107] op_sel_hi:[0,1]
	v_pk_fma_f32 v[100:101], v[12:13], v[106:107], v[108:109]
	v_lshlrev_b32_e32 v106, 16, v70
	v_and_b32_e32 v107, 0xffff0000, v70
	v_lshlrev_b32_e32 v108, 16, v62
	v_and_b32_e32 v109, 0xffff0000, v62
	v_pk_mul_f32 v[106:107], v[96:97], v[106:107] op_sel_hi:[0,1]
	v_pk_fma_f32 v[102:103], v[14:15], v[106:107], v[108:109]
	v_lshlrev_b32_e32 v106, 16, v71
	v_and_b32_e32 v107, 0xffff0000, v71
	v_lshlrev_b32_e32 v108, 16, v63
	v_and_b32_e32 v109, 0xffff0000, v63
	v_pk_mul_f32 v[106:107], v[96:97], v[106:107] op_sel_hi:[0,1]
	v_pk_fma_f32 v[104:105], v[16:17], v[106:107], v[108:109]
	global_store_dwordx4 v23, v[98:101], s[6:7]
	global_store_dwordx4 v23, v[102:105], s[6:7] offset:16
	v_lshlrev_b32_e32 v106, 16, v72
	v_and_b32_e32 v107, 0xffff0000, v72
	v_lshlrev_b32_e32 v108, 16, v64
	v_and_b32_e32 v109, 0xffff0000, v64
	v_pk_mul_f32 v[106:107], v[96:97], v[106:107] op_sel_hi:[0,1]
	v_pk_fma_f32 v[60:61], v[2:3], v[106:107], v[108:109]
	v_lshlrev_b32_e32 v106, 16, v73
	v_and_b32_e32 v107, 0xffff0000, v73
	v_lshlrev_b32_e32 v108, 16, v65
	v_and_b32_e32 v109, 0xffff0000, v65
	v_pk_mul_f32 v[106:107], v[96:97], v[106:107] op_sel_hi:[0,1]
	v_pk_fma_f32 v[62:63], v[4:5], v[106:107], v[108:109]
	v_lshlrev_b32_e32 v106, 16, v74
	v_and_b32_e32 v107, 0xffff0000, v74
	v_lshlrev_b32_e32 v108, 16, v66
	v_and_b32_e32 v109, 0xffff0000, v66
	v_pk_mul_f32 v[106:107], v[96:97], v[106:107] op_sel_hi:[0,1]
	v_pk_fma_f32 v[68:69], v[6:7], v[106:107], v[108:109]
	v_lshlrev_b32_e32 v106, 16, v75
	v_and_b32_e32 v107, 0xffff0000, v75
	v_lshlrev_b32_e32 v108, 16, v67
	v_and_b32_e32 v109, 0xffff0000, v67
	v_pk_mul_f32 v[106:107], v[96:97], v[106:107] op_sel_hi:[0,1]
	v_pk_fma_f32 v[70:71], v[8:9], v[106:107], v[108:109]
	global_store_dwordx4 v23, v[60:63], s[6:7] offset:2048
	global_store_dwordx4 v23, v[68:71], s[6:7] offset:2064
	v_add_u32_e32 v18, 0x7ff800, v18
	v_add_u32_e32 v20, 0x7ff800, v20
	v_add_u32_e32 v21, 0x3ffc, v21
	global_load_dwordx4 v[60:63], v18, s[4:5]
	global_load_dwordx4 v[68:71], v20, s[6:7]
	global_load_dwordx4 v[64:67], v18, s[4:5] offset:1024
	global_load_dwordx4 v[72:75], v20, s[6:7] offset:1024
	global_load_dword v76, v21, s[4:5]
	s_waitcnt vmcnt(27)
; __device__ __forceinline__ float bflo(unsigned w) { return __uint_as_float(w << 16); }
; __device__ __forceinline__ float bfhi(unsigned w) { return __uint_as_float(w & 0xffff0000u); }
; __device__ __forceinline__ void resid_rows(bf16_t* R, const bf16_t* Y, const float* ssqY, const float* g, float* rstd_out, float* outf, bool wf32, int row_lo, int row_hi, int yoff, int gw, int NGW, int lane) {
;     ...
;         for (int k = 0; k < RP; ++k) { const int row = row0 + k * NGW; const bool ok = row < row_hi; const int rw = ok ? row : row0;
;             ssv[k] = ssqY[rw];
; #pragma unroll
;             for (int j = 0; j < 2; ++j) { const int c = 8 * lane + 512 * j; rr[k][j] = *(const u32x4*)(R + (size_t)rw * DM + c); oo[k][j] = *(const u32x4*)(Y + (size_t)(rw - yoff) * DM + c); } }
; #pragma unroll
;         for (int k = 0; k < RP; ++k) { const int row = row0 + k * NGW; if (row < row_hi) {
;             const float rs = __builtin_amdgcn_rsqf(ssv[k] * (1.0f / DM) + RMS_EPS); float s = 0.f;
; #pragma unroll
;             for (int j = 0; j < 2; ++j) { const int c = 8 * lane + 512 * j; const u32x4 r = rr[k][j], o = oo[k][j]; const f32x4 ga = gv[j][0], gb = gv[j][1];
;                 f32x4 ya, yb; ya[0] = bflo(r.x) + bflo(o.x) * rs * ga[0]; ya[1] = bfhi(r.x) + bfhi(o.x) * rs * ga[1]; ya[2] = bflo(r.y) + bflo(o.y) * rs * ga[2]; ya[3] = bfhi(r.y) + bfhi(o.y) * rs * ga[3];
;                 yb[0] = bflo(r.z) + bflo(o.z) * rs * gb[0]; yb[1] = bfhi(r.z) + bfhi(o.z) * rs * gb[1]; yb[2] = bflo(r.w) + bflo(o.w) * rs * gb[2]; yb[3] = bfhi(r.w) + bfhi(o.w) * rs * gb[3];
;                 if (wf32) { *(f32x4*)(outf + (size_t)row * DM + c) = ya; *(f32x4*)(outf + (size_t)row * DM + c + 4) = yb; }
;                 s += (ya[0] * ya[0] + ya[1] * ya[1]) + (ya[2] * ya[2] + ya[3] * ya[3]) + (yb[0] * yb[0] + yb[1] * yb[1]) + (yb[2] * yb[2] + yb[3] * yb[3]);
;                 u32x4 w; w.x = pk2(ya[0], ya[1]); w.y = pk2(ya[2], ya[3]); w.z = pk2(yb[0], yb[1]); w.w = pk2(yb[2], yb[3]); *(u32x4*)(R + (size_t)row * DM + c) = w; }
	v_fmamk_f32 v96, v94, 0x3a800000, v244
	v_rsq_f32_e32 v96, v96
	v_add_u32_e32 v23, 0x1000, v23
	v_lshlrev_b32_e32 v106, 16, v86
	v_and_b32_e32 v107, 0xffff0000, v86
	v_lshlrev_b32_e32 v108, 16, v78
	v_and_b32_e32 v109, 0xffff0000, v78
	v_pk_mul_f32 v[106:107], v[96:97], v[106:107] op_sel_hi:[0,1]
	v_pk_fma_f32 v[98:99], v[10:11], v[106:107], v[108:109]
	v_lshlrev_b32_e32 v106, 16, v87
	v_and_b32_e32 v107, 0xffff0000, v87
	v_lshlrev_b32_e32 v108, 16, v79
	v_and_b32_e32 v109, 0xffff0000, v79
	v_pk_mul_f32 v[106:107], v[96:97], v[106:107] op_sel_hi:[0,1]
	v_pk_fma_f32 v[100:101], v[12:13], v[106:107], v[108:109]
	v_lshlrev_b32_e32 v106, 16, v88
	v_and_b32_e32 v107, 0xffff0000, v88
	v_lshlrev_b32_e32 v108, 16, v80
	v_and_b32_e32 v109, 0xffff0000, v80
	v_pk_mul_f32 v[106:107], v[96:97], v[106:107] op_sel_hi:[0,1]
	v_pk_fma_f32 v[102:103], v[14:15], v[106:107], v[108:109]
	v_lshlrev_b32_e32 v106, 16, v89
	v_and_b32_e32 v107, 0xffff0000, v89
	v_lshlrev_b32_e32 v108, 16, v81
	v_and_b32_e32 v109, 0xffff0000, v81
	v_pk_mul_f32 v[106:107], v[96:97], v[106:107] op_sel_hi:[0,1]
	v_pk_fma_f32 v[104:105], v[16:17], v[106:107], v[108:109]
	global_store_dwordx4 v23, v[98:101], s[6:7]
	global_store_dwordx4 v23, v[102:105], s[6:7] offset:16
	v_lshlrev_b32_e32 v106, 16, v90
	v_and_b32_e32 v107, 0xffff0000, v90
	v_lshlrev_b32_e32 v108, 16, v82
	v_and_b32_e32 v109, 0xffff0000, v82
	v_pk_mul_f32 v[106:107], v[96:97], v[106:107] op_sel_hi:[0,1]
	v_pk_fma_f32 v[78:79], v[2:3], v[106:107], v[108:109]
	v_lshlrev_b32_e32 v106, 16, v91
	v_and_b32_e32 v107, 0xffff0000, v91
	v_lshlrev_b32_e32 v108, 16, v83
	v_and_b32_e32 v109, 0xffff0000, v83
	v_pk_mul_f32 v[106:107], v[96:97], v[106:107] op_sel_hi:[0,1]
	v_pk_fma_f32 v[80:81], v[4:5], v[106:107], v[108:109]
	v_lshlrev_b32_e32 v106, 16, v92
	v_and_b32_e32 v107, 0xffff0000, v92
	v_lshlrev_b32_e32 v108, 16, v84
	v_and_b32_e32 v109, 0xffff0000, v84
	v_pk_mul_f32 v[106:107], v[96:97], v[106:107] op_sel_hi:[0,1]
	v_pk_fma_f32 v[86:87], v[6:7], v[106:107], v[108:109]
	v_lshlrev_b32_e32 v106, 16, v93
	v_and_b32_e32 v107, 0xffff0000, v93
	v_lshlrev_b32_e32 v108, 16, v85
	v_and_b32_e32 v109, 0xffff0000, v85
	v_pk_mul_f32 v[106:107], v[96:97], v[106:107] op_sel_hi:[0,1]
	v_pk_fma_f32 v[88:89], v[8:9], v[106:107], v[108:109]
	global_store_dwordx4 v23, v[78:81], s[6:7] offset:2048
	global_store_dwordx4 v23, v[86:89], s[6:7] offset:2064
	v_add_u32_e32 v18, 0x800, v18
	v_add_u32_e32 v20, 0x800, v20
	v_add_u32_e32 v21, 0x4, v21
	global_load_dwordx4 v[78:81], v18, s[4:5]
	global_load_dwordx4 v[86:89], v20, s[6:7]
	global_load_dwordx4 v[82:85], v18, s[4:5] offset:1024
	global_load_dwordx4 v[90:93], v20, s[6:7] offset:1024
	global_load_dword v94, v21, s[4:5]
	s_waitcnt vmcnt(27)
	v_fmamk_f32 v96, v40, 0x3a800000, v244
	v_rsq_f32_e32 v96, v96
	v_add_u32_e32 v23, 0xfff000, v23
	v_lshlrev_b32_e32 v106, 16, v32
	v_and_b32_e32 v107, 0xffff0000, v32
	v_lshlrev_b32_e32 v108, 16, v24
	v_and_b32_e32 v109, 0xffff0000, v24
	v_pk_mul_f32 v[106:107], v[96:97], v[106:107] op_sel_hi:[0,1]
	v_pk_fma_f32 v[98:99], v[10:11], v[106:107], v[108:109]
	v_lshlrev_b32_e32 v106, 16, v33
	v_and_b32_e32 v107, 0xffff0000, v33
	v_lshlrev_b32_e32 v108, 16, v25
	v_and_b32_e32 v109, 0xffff0000, v25
	v_pk_mul_f32 v[106:107], v[96:97], v[106:107] op_sel_hi:[0,1]
	v_pk_fma_f32 v[100:101], v[12:13], v[106:107], v[108:109]
	v_lshlrev_b32_e32 v106, 16, v34
	v_and_b32_e32 v107, 0xffff0000, v34
	v_lshlrev_b32_e32 v108, 16, v26
	v_and_b32_e32 v109, 0xffff0000, v26
	v_pk_mul_f32 v[106:107], v[96:97], v[106:107] op_sel_hi:[0,1]
	v_pk_fma_f32 v[102:103], v[14:15], v[106:107], v[108:109]
	v_lshlrev_b32_e32 v106, 16, v35
	v_and_b32_e32 v107, 0xffff0000, v35
	v_lshlrev_b32_e32 v108, 16, v27
	v_and_b32_e32 v109, 0xffff0000, v27
	v_pk_mul_f32 v[106:107], v[96:97], v[106:107] op_sel_hi:[0,1]
	v_pk_fma_f32 v[104:105], v[16:17], v[106:107], v[108:109]
	global_store_dwordx4 v23, v[98:101], s[6:7]
	global_store_dwordx4 v23, v[102:105], s[6:7] offset:16
	v_lshlrev_b32_e32 v106, 16, v36
	v_and_b32_e32 v107, 0xffff0000, v36
	v_lshlrev_b32_e32 v108, 16, v28
	v_and_b32_e32 v109, 0xffff0000, v28
	v_pk_mul_f32 v[106:107], v[96:97], v[106:107] op_sel_hi:[0,1]
	v_pk_fma_f32 v[24:25], v[2:3], v[106:107], v[108:109]
	v_lshlrev_b32_e32 v106, 16, v37
	v_and_b32_e32 v107, 0xffff0000, v37
	v_lshlrev_b32_e32 v108, 16, v29
	v_and_b32_e32 v109, 0xffff0000, v29
	v_pk_mul_f32 v[106:107], v[96:97], v[106:107] op_sel_hi:[0,1]
	v_pk_fma_f32 v[26:27], v[4:5], v[106:107], v[108:109]
	v_lshlrev_b32_e32 v106, 16, v38
	v_and_b32_e32 v107, 0xffff0000, v38
	v_lshlrev_b32_e32 v108, 16, v30
	v_and_b32_e32 v109, 0xffff0000, v30
	v_pk_mul_f32 v[106:107], v[96:97], v[106:107] op_sel_hi:[0,1]
	v_pk_fma_f32 v[32:33], v[6:7], v[106:107], v[108:109]
	v_lshlrev_b32_e32 v106, 16, v39
	v_and_b32_e32 v107, 0xffff0000, v39
	v_lshlrev_b32_e32 v108, 16, v31
	v_and_b32_e32 v109, 0xffff0000, v31
	v_pk_mul_f32 v[106:107], v[96:97], v[106:107] op_sel_hi:[0,1]
	v_pk_fma_f32 v[34:35], v[8:9], v[106:107], v[108:109]
	global_store_dwordx4 v23, v[24:27], s[6:7] offset:2048
	global_store_dwordx4 v23, v[32:35], s[6:7] offset:2064
	v_add_u32_e32 v18, 0xfc7ff800, v18
	s_lshl_b32 s18, s13, 11
	v_subrev_u32_e32 v18, s18, v18
	v_add_u32_e32 v20, 0xb7ff800, v20
	s_lshl_b32 s18, s13, 11
	v_subrev_u32_e32 v20, s18, v20
	v_add_u32_e32 v21, 0xfffe3ffc, v21
	s_lshl_b32 s18, s13, 2
	v_subrev_u32_e32 v21, s18, v21
	global_load_dwordx4 v[24:27], v18, s[4:5]
	global_load_dwordx4 v[32:35], v20, s[4:5]
	global_load_dwordx4 v[28:31], v18, s[4:5] offset:1024
	global_load_dwordx4 v[36:39], v20, s[4:5] offset:1024
	global_load_dword v40, v21, s[4:5]
	s_waitcnt vmcnt(27)
; __device__ __forceinline__ float bflo(unsigned w) { return __uint_as_float(w << 16); }
; __device__ __forceinline__ float bfhi(unsigned w) { return __uint_as_float(w & 0xffff0000u); }
; __device__ __forceinline__ void resid_rows(bf16_t* R, const bf16_t* Y, const float* ssqY, const float* g, float* rstd_out, float* outf, bool wf32, int row_lo, int row_hi, int yoff, int gw, int NGW, int lane) {
;     ...
;         for (int k = 0; k < RP; ++k) { const int row = row0 + k * NGW; const bool ok = row < row_hi; const int rw = ok ? row : row0;
;             ssv[k] = ssqY[rw];
; #pragma unroll
;             for (int j = 0; j < 2; ++j) { const int c = 8 * lane + 512 * j; rr[k][j] = *(const u32x4*)(R + (size_t)rw * DM + c); oo[k][j] = *(const u32x4*)(Y + (size_t)(rw - yoff) * DM + c); } }
; #pragma unroll
;         for (int k = 0; k < RP; ++k) { const int row = row0 + k * NGW; if (row < row_hi) {
;             const float rs = __builtin_amdgcn_rsqf(ssv[k] * (1.0f / DM) + RMS_EPS); float s = 0.f;
; #pragma unroll
;             for (int j = 0; j < 2; ++j) { const int c = 8 * lane + 512 * j; const u32x4 r = rr[k][j], o = oo[k][j]; const f32x4 ga = gv[j][0], gb = gv[j][1];
;                 f32x4 ya, yb; ya[0] = bflo(r.x) + bflo(o.x) * rs * ga[0]; ya[1] = bfhi(r.x) + bfhi(o.x) * rs * ga[1]; ya[2] = bflo(r.y) + bflo(o.y) * rs * ga[2]; ya[3] = bfhi(r.y) + bfhi(o.y) * rs * ga[3];
;                 yb[0] = bflo(r.z) + bflo(o.z) * rs * gb[0]; yb[1] = bfhi(r.z) + bfhi(o.z) * rs * gb[1]; yb[2] = bflo(r.w) + bflo(o.w) * rs * gb[2]; yb[3] = bfhi(r.w) + bfhi(o.w) * rs * gb[3];
;                 if (wf32) { *(f32x4*)(outf + (size_t)row * DM + c) = ya; *(f32x4*)(outf + (size_t)row * DM + c + 4) = yb; }
;                 s += (ya[0] * ya[0] + ya[1] * ya[1]) + (ya[2] * ya[2] + ya[3] * ya[3]) + (yb[0] * yb[0] + yb[1] * yb[1]) + (yb[2] * yb[2] + yb[3] * yb[3]);
;                 u32x4 w; w.x = pk2(ya[0], ya[1]); w.y = pk2(ya[2], ya[3]); w.z = pk2(yb[0], yb[1]); w.w = pk2(yb[2], yb[3]); *(u32x4*)(R + (size_t)row * DM + c) = w; }
	v_fmamk_f32 v96, v58, 0x3a800000, v244
	v_rsq_f32_e32 v96, v96
	v_add_u32_e32 v23, 0x1000, v23
	v_lshlrev_b32_e32 v106, 16, v50
	v_and_b32_e32 v107, 0xffff0000, v50
	v_lshlrev_b32_e32 v108, 16, v42
	v_and_b32_e32 v109, 0xffff0000, v42
	v_pk_mul_f32 v[106:107], v[96:97], v[106:107] op_sel_hi:[0,1]
	v_pk_fma_f32 v[98:99], v[10:11], v[106:107], v[108:109]
	v_lshlrev_b32_e32 v106, 16, v51
	v_and_b32_e32 v107, 0xffff0000, v51
	v_lshlrev_b32_e32 v108, 16, v43
	v_and_b32_e32 v109, 0xffff0000, v43
	v_pk_mul_f32 v[106:107], v[96:97], v[106:107] op_sel_hi:[0,1]
	v_pk_fma_f32 v[100:101], v[12:13], v[106:107], v[108:109]
	v_lshlrev_b32_e32 v106, 16, v52
	v_and_b32_e32 v107, 0xffff0000, v52
	v_lshlrev_b32_e32 v108, 16, v44
	v_and_b32_e32 v109, 0xffff0000, v44
	v_pk_mul_f32 v[106:107], v[96:97], v[106:107] op_sel_hi:[0,1]
	v_pk_fma_f32 v[102:103], v[14:15], v[106:107], v[108:109]
	v_lshlrev_b32_e32 v106, 16, v53
	v_and_b32_e32 v107, 0xffff0000, v53
	v_lshlrev_b32_e32 v108, 16, v45
	v_and_b32_e32 v109, 0xffff0000, v45
	v_pk_mul_f32 v[106:107], v[96:97], v[106:107] op_sel_hi:[0,1]
	v_pk_fma_f32 v[104:105], v[16:17], v[106:107], v[108:109]
	global_store_dwordx4 v23, v[98:101], s[6:7]
	global_store_dwordx4 v23, v[102:105], s[6:7] offset:16
	v_lshlrev_b32_e32 v106, 16, v54
	v_and_b32_e32 v107, 0xffff0000, v54
	v_lshlrev_b32_e32 v108, 16, v46
	v_and_b32_e32 v109, 0xffff0000, v46
	v_pk_mul_f32 v[106:107], v[96:97], v[106:107] op_sel_hi:[0,1]
	v_pk_fma_f32 v[42:43], v[2:3], v[106:107], v[108:109]
	v_lshlrev_b32_e32 v106, 16, v55
	v_and_b32_e32 v107, 0xffff0000, v55
	v_lshlrev_b32_e32 v108, 16, v47
	v_and_b32_e32 v109, 0xffff0000, v47
	v_pk_mul_f32 v[106:107], v[96:97], v[106:107] op_sel_hi:[0,1]
	v_pk_fma_f32 v[44:45], v[4:5], v[106:107], v[108:109]
	v_lshlrev_b32_e32 v106, 16, v56
	v_and_b32_e32 v107, 0xffff0000, v56
	v_lshlrev_b32_e32 v108, 16, v48
	v_and_b32_e32 v109, 0xffff0000, v48
	v_pk_mul_f32 v[106:107], v[96:97], v[106:107] op_sel_hi:[0,1]
	v_pk_fma_f32 v[50:51], v[6:7], v[106:107], v[108:109]
	v_lshlrev_b32_e32 v106, 16, v57
	v_and_b32_e32 v107, 0xffff0000, v57
	v_lshlrev_b32_e32 v108, 16, v49
	v_and_b32_e32 v109, 0xffff0000, v49
	v_pk_mul_f32 v[106:107], v[96:97], v[106:107] op_sel_hi:[0,1]
	v_pk_fma_f32 v[52:53], v[8:9], v[106:107], v[108:109]
	global_store_dwordx4 v23, v[42:45], s[6:7] offset:2048
	global_store_dwordx4 v23, v[50:53], s[6:7] offset:2064
	v_add_u32_e32 v18, 0x400000, v18
	v_add_u32_e32 v20, 0x400000, v20
	v_add_u32_e32 v21, 0x2000, v21
	global_load_dwordx4 v[42:45], v18, s[4:5]
	global_load_dwordx4 v[50:53], v20, s[4:5]
	global_load_dwordx4 v[46:49], v18, s[4:5] offset:1024
	global_load_dwordx4 v[54:57], v20, s[4:5] offset:1024
	global_load_dword v58, v21, s[4:5]
	s_waitcnt vmcnt(27)
	v_fmamk_f32 v96, v76, 0x3a800000, v244
	v_rsq_f32_e32 v96, v96
	v_add_u32_e32 v23, 0xfff000, v23
	v_lshlrev_b32_e32 v106, 16, v68
	v_and_b32_e32 v107, 0xffff0000, v68
	v_lshlrev_b32_e32 v108, 16, v60
	v_and_b32_e32 v109, 0xffff0000, v60
	v_pk_mul_f32 v[106:107], v[96:97], v[106:107] op_sel_hi:[0,1]
	v_pk_fma_f32 v[98:99], v[10:11], v[106:107], v[108:109]
	v_lshlrev_b32_e32 v106, 16, v69
	v_and_b32_e32 v107, 0xffff0000, v69
	v_lshlrev_b32_e32 v108, 16, v61
	v_and_b32_e32 v109, 0xffff0000, v61
	v_pk_mul_f32 v[106:107], v[96:97], v[106:107] op_sel_hi:[0,1]
	v_pk_fma_f32 v[100:101], v[12:13], v[106:107], v[108:109]
	v_lshlrev_b32_e32 v106, 16, v70
	v_and_b32_e32 v107, 0xffff0000, v70
	v_lshlrev_b32_e32 v108, 16, v62
	v_and_b32_e32 v109, 0xffff0000, v62
	v_pk_mul_f32 v[106:107], v[96:97], v[106:107] op_sel_hi:[0,1]
	v_pk_fma_f32 v[102:103], v[14:15], v[106:107], v[108:109]
	v_lshlrev_b32_e32 v106, 16, v71
	v_and_b32_e32 v107, 0xffff0000, v71
	v_lshlrev_b32_e32 v108, 16, v63
	v_and_b32_e32 v109, 0xffff0000, v63
	v_pk_mul_f32 v[106:107], v[96:97], v[106:107] op_sel_hi:[0,1]
	v_pk_fma_f32 v[104:105], v[16:17], v[106:107], v[108:109]
	global_store_dwordx4 v23, v[98:101], s[6:7]
	global_store_dwordx4 v23, v[102:105], s[6:7] offset:16
	v_lshlrev_b32_e32 v106, 16, v72
	v_and_b32_e32 v107, 0xffff0000, v72
	v_lshlrev_b32_e32 v108, 16, v64
	v_and_b32_e32 v109, 0xffff0000, v64
	v_pk_mul_f32 v[106:107], v[96:97], v[106:107] op_sel_hi:[0,1]
	v_pk_fma_f32 v[60:61], v[2:3], v[106:107], v[108:109]
	v_lshlrev_b32_e32 v106, 16, v73
	v_and_b32_e32 v107, 0xffff0000, v73
	v_lshlrev_b32_e32 v108, 16, v65
	v_and_b32_e32 v109, 0xffff0000, v65
	v_pk_mul_f32 v[106:107], v[96:97], v[106:107] op_sel_hi:[0,1]
	v_pk_fma_f32 v[62:63], v[4:5], v[106:107], v[108:109]
	v_lshlrev_b32_e32 v106, 16, v74
	v_and_b32_e32 v107, 0xffff0000, v74
	v_lshlrev_b32_e32 v108, 16, v66
	v_and_b32_e32 v109, 0xffff0000, v66
	v_pk_mul_f32 v[106:107], v[96:97], v[106:107] op_sel_hi:[0,1]
	v_pk_fma_f32 v[68:69], v[6:7], v[106:107], v[108:109]
	v_lshlrev_b32_e32 v106, 16, v75
	v_and_b32_e32 v107, 0xffff0000, v75
	v_lshlrev_b32_e32 v108, 16, v67
	v_and_b32_e32 v109, 0xffff0000, v67
	v_pk_mul_f32 v[106:107], v[96:97], v[106:107] op_sel_hi:[0,1]
	v_pk_fma_f32 v[70:71], v[8:9], v[106:107], v[108:109]
	global_store_dwordx4 v23, v[60:63], s[6:7] offset:2048
	global_store_dwordx4 v23, v[68:71], s[6:7] offset:2064
	v_add_u32_e32 v18, 0x400000, v18
	v_add_u32_e32 v20, 0x400000, v20
	v_add_u32_e32 v21, 0x2000, v21
	global_load_dwordx4 v[60:63], v18, s[4:5]
	global_load_dwordx4 v[68:71], v20, s[4:5]
	global_load_dwordx4 v[64:67], v18, s[4:5] offset:1024
	global_load_dwordx4 v[72:75], v20, s[4:5] offset:1024
	global_load_dword v76, v21, s[4:5]
	s_waitcnt vmcnt(27)
; __device__ __forceinline__ float bflo(unsigned w) { return __uint_as_float(w << 16); }
; __device__ __forceinline__ float bfhi(unsigned w) { return __uint_as_float(w & 0xffff0000u); }
; __device__ __forceinline__ void resid_rows(bf16_t* R, const bf16_t* Y, const float* ssqY, const float* g, float* rstd_out, float* outf, bool wf32, int row_lo, int row_hi, int yoff, int gw, int NGW, int lane) {
;     ...
;         for (int k = 0; k < RP; ++k) { const int row = row0 + k * NGW; const bool ok = row < row_hi; const int rw = ok ? row : row0;
;             ssv[k] = ssqY[rw];
; #pragma unroll
;             for (int j = 0; j < 2; ++j) { const int c = 8 * lane + 512 * j; rr[k][j] = *(const u32x4*)(R + (size_t)rw * DM + c); oo[k][j] = *(const u32x4*)(Y + (size_t)(rw - yoff) * DM + c); } }
; #pragma unroll
;         for (int k = 0; k < RP; ++k) { const int row = row0 + k * NGW; if (row < row_hi) {
;             const float rs = __builtin_amdgcn_rsqf(ssv[k] * (1.0f / DM) + RMS_EPS); float s = 0.f;
; #pragma unroll
;             for (int j = 0; j < 2; ++j) { const int c = 8 * lane + 512 * j; const u32x4 r = rr[k][j], o = oo[k][j]; const f32x4 ga = gv[j][0], gb = gv[j][1];
;                 f32x4 ya, yb; ya[0] = bflo(r.x) + bflo(o.x) * rs * ga[0]; ya[1] = bfhi(r.x) + bfhi(o.x) * rs * ga[1]; ya[2] = bflo(r.y) + bflo(o.y) * rs * ga[2]; ya[3] = bfhi(r.y) + bfhi(o.y) * rs * ga[3];
;                 yb[0] = bflo(r.z) + bflo(o.z) * rs * gb[0]; yb[1] = bfhi(r.z) + bfhi(o.z) * rs * gb[1]; yb[2] = bflo(r.w) + bflo(o.w) * rs * gb[2]; yb[3] = bfhi(r.w) + bfhi(o.w) * rs * gb[3];
;                 if (wf32) { *(f32x4*)(outf + (size_t)row * DM + c) = ya; *(f32x4*)(outf + (size_t)row * DM + c + 4) = yb; }
;                 s += (ya[0] * ya[0] + ya[1] * ya[1]) + (ya[2] * ya[2] + ya[3] * ya[3]) + (yb[0] * yb[0] + yb[1] * yb[1]) + (yb[2] * yb[2] + yb[3] * yb[3]);
;                 u32x4 w; w.x = pk2(ya[0], ya[1]); w.y = pk2(ya[2], ya[3]); w.z = pk2(yb[0], yb[1]); w.w = pk2(yb[2], yb[3]); *(u32x4*)(R + (size_t)row * DM + c) = w; }
	v_fmamk_f32 v96, v94, 0x3a800000, v244
	v_rsq_f32_e32 v96, v96
	v_add_u32_e32 v23, 0x1000, v23
	v_lshlrev_b32_e32 v106, 16, v86
	v_and_b32_e32 v107, 0xffff0000, v86
	v_lshlrev_b32_e32 v108, 16, v78
	v_and_b32_e32 v109, 0xffff0000, v78
	v_pk_mul_f32 v[106:107], v[96:97], v[106:107] op_sel_hi:[0,1]
	v_pk_fma_f32 v[98:99], v[10:11], v[106:107], v[108:109]
	v_lshlrev_b32_e32 v106, 16, v87
	v_and_b32_e32 v107, 0xffff0000, v87
	v_lshlrev_b32_e32 v108, 16, v79
	v_and_b32_e32 v109, 0xffff0000, v79
	v_pk_mul_f32 v[106:107], v[96:97], v[106:107] op_sel_hi:[0,1]
	v_pk_fma_f32 v[100:101], v[12:13], v[106:107], v[108:109]
	v_lshlrev_b32_e32 v106, 16, v88
	v_and_b32_e32 v107, 0xffff0000, v88
	v_lshlrev_b32_e32 v108, 16, v80
	v_and_b32_e32 v109, 0xffff0000, v80
	v_pk_mul_f32 v[106:107], v[96:97], v[106:107] op_sel_hi:[0,1]
	v_pk_fma_f32 v[102:103], v[14:15], v[106:107], v[108:109]
	v_lshlrev_b32_e32 v106, 16, v89
	v_and_b32_e32 v107, 0xffff0000, v89
	v_lshlrev_b32_e32 v108, 16, v81
	v_and_b32_e32 v109, 0xffff0000, v81
	v_pk_mul_f32 v[106:107], v[96:97], v[106:107] op_sel_hi:[0,1]
	v_pk_fma_f32 v[104:105], v[16:17], v[106:107], v[108:109]
	global_store_dwordx4 v23, v[98:101], s[6:7]
	global_store_dwordx4 v23, v[102:105], s[6:7] offset:16
	v_lshlrev_b32_e32 v106, 16, v90
	v_and_b32_e32 v107, 0xffff0000, v90
	v_lshlrev_b32_e32 v108, 16, v82
	v_and_b32_e32 v109, 0xffff0000, v82
	v_pk_mul_f32 v[106:107], v[96:97], v[106:107] op_sel_hi:[0,1]
	v_pk_fma_f32 v[78:79], v[2:3], v[106:107], v[108:109]
	v_lshlrev_b32_e32 v106, 16, v91
	v_and_b32_e32 v107, 0xffff0000, v91
	v_lshlrev_b32_e32 v108, 16, v83
	v_and_b32_e32 v109, 0xffff0000, v83
	v_pk_mul_f32 v[106:107], v[96:97], v[106:107] op_sel_hi:[0,1]
	v_pk_fma_f32 v[80:81], v[4:5], v[106:107], v[108:109]
	v_lshlrev_b32_e32 v106, 16, v92
	v_and_b32_e32 v107, 0xffff0000, v92
	v_lshlrev_b32_e32 v108, 16, v84
	v_and_b32_e32 v109, 0xffff0000, v84
	v_pk_mul_f32 v[106:107], v[96:97], v[106:107] op_sel_hi:[0,1]
	v_pk_fma_f32 v[86:87], v[6:7], v[106:107], v[108:109]
	v_lshlrev_b32_e32 v106, 16, v93
	v_and_b32_e32 v107, 0xffff0000, v93
	v_lshlrev_b32_e32 v108, 16, v85
	v_and_b32_e32 v109, 0xffff0000, v85
	v_pk_mul_f32 v[106:107], v[96:97], v[106:107] op_sel_hi:[0,1]
	v_pk_fma_f32 v[88:89], v[8:9], v[106:107], v[108:109]
	global_store_dwordx4 v23, v[78:81], s[6:7] offset:2048
	global_store_dwordx4 v23, v[86:89], s[6:7] offset:2064
	v_add_u32_e32 v18, 0x400000, v18
	v_add_u32_e32 v20, 0x400000, v20
	v_add_u32_e32 v21, 0x2000, v21
	global_load_dwordx4 v[78:81], v18, s[4:5]
	global_load_dwordx4 v[86:89], v20, s[4:5]
	global_load_dwordx4 v[82:85], v18, s[4:5] offset:1024
	global_load_dwordx4 v[90:93], v20, s[4:5] offset:1024
	global_load_dword v94, v21, s[4:5]
	s_waitcnt vmcnt(27)
	v_fmamk_f32 v96, v40, 0x3a800000, v244
	v_rsq_f32_e32 v96, v96
	v_add_u32_e32 v23, 0xf8fff000, v23
	s_lshl_b32 s18, s13, 12
	v_subrev_u32_e32 v23, s18, v23
	v_lshlrev_b32_e32 v106, 16, v32
	v_and_b32_e32 v107, 0xffff0000, v32
	v_lshlrev_b32_e32 v108, 16, v24
	v_and_b32_e32 v109, 0xffff0000, v24
	v_pk_mul_f32 v[106:107], v[96:97], v[106:107] op_sel_hi:[0,1]
	v_pk_fma_f32 v[98:99], v[10:11], v[106:107], v[108:109]
	v_lshlrev_b32_e32 v106, 16, v33
	v_and_b32_e32 v107, 0xffff0000, v33
	v_lshlrev_b32_e32 v108, 16, v25
	v_and_b32_e32 v109, 0xffff0000, v25
	v_pk_mul_f32 v[106:107], v[96:97], v[106:107] op_sel_hi:[0,1]
	v_pk_fma_f32 v[100:101], v[12:13], v[106:107], v[108:109]
	v_lshlrev_b32_e32 v106, 16, v34
	v_and_b32_e32 v107, 0xffff0000, v34
	v_lshlrev_b32_e32 v108, 16, v26
	v_and_b32_e32 v109, 0xffff0000, v26
	v_pk_mul_f32 v[106:107], v[96:97], v[106:107] op_sel_hi:[0,1]
	v_pk_fma_f32 v[102:103], v[14:15], v[106:107], v[108:109]
	v_lshlrev_b32_e32 v106, 16, v35
	v_and_b32_e32 v107, 0xffff0000, v35
	v_lshlrev_b32_e32 v108, 16, v27
	v_and_b32_e32 v109, 0xffff0000, v27
	v_pk_mul_f32 v[106:107], v[96:97], v[106:107] op_sel_hi:[0,1]
	v_pk_fma_f32 v[104:105], v[16:17], v[106:107], v[108:109]
	global_store_dwordx4 v23, v[98:101], s[6:7]
	global_store_dwordx4 v23, v[102:105], s[6:7] offset:16
	v_lshlrev_b32_e32 v106, 16, v36
	v_and_b32_e32 v107, 0xffff0000, v36
	v_lshlrev_b32_e32 v108, 16, v28
	v_and_b32_e32 v109, 0xffff0000, v28
	v_pk_mul_f32 v[106:107], v[96:97], v[106:107] op_sel_hi:[0,1]
	v_pk_fma_f32 v[24:25], v[2:3], v[106:107], v[108:109]
	v_lshlrev_b32_e32 v106, 16, v37
	v_and_b32_e32 v107, 0xffff0000, v37
	v_lshlrev_b32_e32 v108, 16, v29
	v_and_b32_e32 v109, 0xffff0000, v29
	v_pk_mul_f32 v[106:107], v[96:97], v[106:107] op_sel_hi:[0,1]
	v_pk_fma_f32 v[26:27], v[4:5], v[106:107], v[108:109]
	v_lshlrev_b32_e32 v106, 16, v38
	v_and_b32_e32 v107, 0xffff0000, v38
	v_lshlrev_b32_e32 v108, 16, v30
	v_and_b32_e32 v109, 0xffff0000, v30
	v_pk_mul_f32 v[106:107], v[96:97], v[106:107] op_sel_hi:[0,1]
	v_pk_fma_f32 v[32:33], v[6:7], v[106:107], v[108:109]
	v_lshlrev_b32_e32 v106, 16, v39
	v_and_b32_e32 v107, 0xffff0000, v39
	v_lshlrev_b32_e32 v108, 16, v31
	v_and_b32_e32 v109, 0xffff0000, v31
	v_pk_mul_f32 v[106:107], v[96:97], v[106:107] op_sel_hi:[0,1]
	v_pk_fma_f32 v[34:35], v[8:9], v[106:107], v[108:109]
	global_store_dwordx4 v23, v[24:27], s[6:7] offset:2048
	global_store_dwordx4 v23, v[32:35], s[6:7] offset:2064
	v_add_u32_e32 v18, 0x400000, v18
	v_add_u32_e32 v20, 0x400000, v20
	v_add_u32_e32 v21, 0x2000, v21
	global_load_dwordx4 v[24:27], v18, s[4:5]
	global_load_dwordx4 v[32:35], v20, s[4:5]
	global_load_dwordx4 v[28:31], v18, s[4:5] offset:1024
	global_load_dwordx4 v[36:39], v20, s[4:5] offset:1024
	global_load_dword v40, v21, s[4:5]
	s_waitcnt vmcnt(27)
; __device__ __forceinline__ float bflo(unsigned w) { return __uint_as_float(w << 16); }
; __device__ __forceinline__ float bfhi(unsigned w) { return __uint_as_float(w & 0xffff0000u); }
; __device__ __forceinline__ void resid_rows(bf16_t* R, const bf16_t* Y, const float* ssqY, const float* g, float* rstd_out, float* outf, bool wf32, int row_lo, int row_hi, int yoff, int gw, int NGW, int lane) {
;     ...
;         for (int k = 0; k < RP; ++k) { const int row = row0 + k * NGW; const bool ok = row < row_hi; const int rw = ok ? row : row0;
;             ssv[k] = ssqY[rw];
; #pragma unroll
;             for (int j = 0; j < 2; ++j) { const int c = 8 * lane + 512 * j; rr[k][j] = *(const u32x4*)(R + (size_t)rw * DM + c); oo[k][j] = *(const u32x4*)(Y + (size_t)(rw - yoff) * DM + c); } }
; #pragma unroll
;         for (int k = 0; k < RP; ++k) { const int row = row0 + k * NGW; if (row < row_hi) {
;             const float rs = __builtin_amdgcn_rsqf(ssv[k] * (1.0f / DM) + RMS_EPS); float s = 0.f;
; #pragma unroll
;             for (int j = 0; j < 2; ++j) { const int c = 8 * lane + 512 * j; const u32x4 r = rr[k][j], o = oo[k][j]; const f32x4 ga = gv[j][0], gb = gv[j][1];
;                 f32x4 ya, yb; ya[0] = bflo(r.x) + bflo(o.x) * rs * ga[0]; ya[1] = bfhi(r.x) + bfhi(o.x) * rs * ga[1]; ya[2] = bflo(r.y) + bflo(o.y) * rs * ga[2]; ya[3] = bfhi(r.y) + bfhi(o.y) * rs * ga[3];
;                 yb[0] = bflo(r.z) + bflo(o.z) * rs * gb[0]; yb[1] = bfhi(r.z) + bfhi(o.z) * rs * gb[1]; yb[2] = bflo(r.w) + bflo(o.w) * rs * gb[2]; yb[3] = bfhi(r.w) + bfhi(o.w) * rs * gb[3];
;                 if (wf32) { *(f32x4*)(outf + (size_t)row * DM + c) = ya; *(f32x4*)(outf + (size_t)row * DM + c + 4) = yb; }
;                 s += (ya[0] * ya[0] + ya[1] * ya[1]) + (ya[2] * ya[2] + ya[3] * ya[3]) + (yb[0] * yb[0] + yb[1] * yb[1]) + (yb[2] * yb[2] + yb[3] * yb[3]);
;                 u32x4 w; w.x = pk2(ya[0], ya[1]); w.y = pk2(ya[2], ya[3]); w.z = pk2(yb[0], yb[1]); w.w = pk2(yb[2], yb[3]); *(u32x4*)(R + (size_t)row * DM + c) = w; }
	v_fmamk_f32 v96, v58, 0x3a800000, v244
	v_rsq_f32_e32 v96, v96
	v_add_u32_e32 v23, 0x800000, v23
	v_lshlrev_b32_e32 v106, 16, v50
	v_and_b32_e32 v107, 0xffff0000, v50
	v_lshlrev_b32_e32 v108, 16, v42
	v_and_b32_e32 v109, 0xffff0000, v42
	v_pk_mul_f32 v[106:107], v[96:97], v[106:107] op_sel_hi:[0,1]
	v_pk_fma_f32 v[98:99], v[10:11], v[106:107], v[108:109]
	v_lshlrev_b32_e32 v106, 16, v51
	v_and_b32_e32 v107, 0xffff0000, v51
	v_lshlrev_b32_e32 v108, 16, v43
	v_and_b32_e32 v109, 0xffff0000, v43
	v_pk_mul_f32 v[106:107], v[96:97], v[106:107] op_sel_hi:[0,1]
	v_pk_fma_f32 v[100:101], v[12:13], v[106:107], v[108:109]
	v_lshlrev_b32_e32 v106, 16, v52
	v_and_b32_e32 v107, 0xffff0000, v52
	v_lshlrev_b32_e32 v108, 16, v44
	v_and_b32_e32 v109, 0xffff0000, v44
	v_pk_mul_f32 v[106:107], v[96:97], v[106:107] op_sel_hi:[0,1]
	v_pk_fma_f32 v[102:103], v[14:15], v[106:107], v[108:109]
	v_lshlrev_b32_e32 v106, 16, v53
	v_and_b32_e32 v107, 0xffff0000, v53
	v_lshlrev_b32_e32 v108, 16, v45
	v_and_b32_e32 v109, 0xffff0000, v45
	v_pk_mul_f32 v[106:107], v[96:97], v[106:107] op_sel_hi:[0,1]
	v_pk_fma_f32 v[104:105], v[16:17], v[106:107], v[108:109]
	global_store_dwordx4 v23, v[98:101], s[6:7]
	global_store_dwordx4 v23, v[102:105], s[6:7] offset:16
	v_lshlrev_b32_e32 v106, 16, v54
	v_and_b32_e32 v107, 0xffff0000, v54
	v_lshlrev_b32_e32 v108, 16, v46
	v_and_b32_e32 v109, 0xffff0000, v46
	v_pk_mul_f32 v[106:107], v[96:97], v[106:107] op_sel_hi:[0,1]
	v_pk_fma_f32 v[42:43], v[2:3], v[106:107], v[108:109]
	v_lshlrev_b32_e32 v106, 16, v55
	v_and_b32_e32 v107, 0xffff0000, v55
	v_lshlrev_b32_e32 v108, 16, v47
	v_and_b32_e32 v109, 0xffff0000, v47
	v_pk_mul_f32 v[106:107], v[96:97], v[106:107] op_sel_hi:[0,1]
	v_pk_fma_f32 v[44:45], v[4:5], v[106:107], v[108:109]
	v_lshlrev_b32_e32 v106, 16, v56
	v_and_b32_e32 v107, 0xffff0000, v56
	v_lshlrev_b32_e32 v108, 16, v48
	v_and_b32_e32 v109, 0xffff0000, v48
	v_pk_mul_f32 v[106:107], v[96:97], v[106:107] op_sel_hi:[0,1]
	v_pk_fma_f32 v[50:51], v[6:7], v[106:107], v[108:109]
	v_lshlrev_b32_e32 v106, 16, v57
	v_and_b32_e32 v107, 0xffff0000, v57
	v_lshlrev_b32_e32 v108, 16, v49
	v_and_b32_e32 v109, 0xffff0000, v49
	v_pk_mul_f32 v[106:107], v[96:97], v[106:107] op_sel_hi:[0,1]
	v_pk_fma_f32 v[52:53], v[8:9], v[106:107], v[108:109]
	global_store_dwordx4 v23, v[42:45], s[6:7] offset:2048
	global_store_dwordx4 v23, v[50:53], s[6:7] offset:2064
	v_add_u32_e32 v18, 0x400000, v18
	v_add_u32_e32 v20, 0x400000, v20
	v_add_u32_e32 v21, 0x2000, v21
	global_load_dwordx4 v[42:45], v18, s[4:5]
	global_load_dwordx4 v[50:53], v20, s[4:5]
	global_load_dwordx4 v[46:49], v18, s[4:5] offset:1024
	global_load_dwordx4 v[54:57], v20, s[4:5] offset:1024
	global_load_dword v58, v21, s[4:5]
	s_waitcnt vmcnt(27)
	v_fmamk_f32 v96, v76, 0x3a800000, v244
	v_rsq_f32_e32 v96, v96
	v_add_u32_e32 v23, 0x800000, v23
	v_lshlrev_b32_e32 v106, 16, v68
	v_and_b32_e32 v107, 0xffff0000, v68
	v_lshlrev_b32_e32 v108, 16, v60
	v_and_b32_e32 v109, 0xffff0000, v60
	v_pk_mul_f32 v[106:107], v[96:97], v[106:107] op_sel_hi:[0,1]
	v_pk_fma_f32 v[98:99], v[10:11], v[106:107], v[108:109]
	v_lshlrev_b32_e32 v106, 16, v69
	v_and_b32_e32 v107, 0xffff0000, v69
	v_lshlrev_b32_e32 v108, 16, v61
	v_and_b32_e32 v109, 0xffff0000, v61
	v_pk_mul_f32 v[106:107], v[96:97], v[106:107] op_sel_hi:[0,1]
	v_pk_fma_f32 v[100:101], v[12:13], v[106:107], v[108:109]
	v_lshlrev_b32_e32 v106, 16, v70
	v_and_b32_e32 v107, 0xffff0000, v70
	v_lshlrev_b32_e32 v108, 16, v62
	v_and_b32_e32 v109, 0xffff0000, v62
	v_pk_mul_f32 v[106:107], v[96:97], v[106:107] op_sel_hi:[0,1]
	v_pk_fma_f32 v[102:103], v[14:15], v[106:107], v[108:109]
	v_lshlrev_b32_e32 v106, 16, v71
	v_and_b32_e32 v107, 0xffff0000, v71
	v_lshlrev_b32_e32 v108, 16, v63
	v_and_b32_e32 v109, 0xffff0000, v63
	v_pk_mul_f32 v[106:107], v[96:97], v[106:107] op_sel_hi:[0,1]
	v_pk_fma_f32 v[104:105], v[16:17], v[106:107], v[108:109]
	global_store_dwordx4 v23, v[98:101], s[6:7]
	global_store_dwordx4 v23, v[102:105], s[6:7] offset:16
	v_lshlrev_b32_e32 v106, 16, v72
	v_and_b32_e32 v107, 0xffff0000, v72
	v_lshlrev_b32_e32 v108, 16, v64
	v_and_b32_e32 v109, 0xffff0000, v64
	v_pk_mul_f32 v[106:107], v[96:97], v[106:107] op_sel_hi:[0,1]
	v_pk_fma_f32 v[60:61], v[2:3], v[106:107], v[108:109]
	v_lshlrev_b32_e32 v106, 16, v73
	v_and_b32_e32 v107, 0xffff0000, v73
	v_lshlrev_b32_e32 v108, 16, v65
	v_and_b32_e32 v109, 0xffff0000, v65
	v_pk_mul_f32 v[106:107], v[96:97], v[106:107] op_sel_hi:[0,1]
	v_pk_fma_f32 v[62:63], v[4:5], v[106:107], v[108:109]
	v_lshlrev_b32_e32 v106, 16, v74
	v_and_b32_e32 v107, 0xffff0000, v74
	v_lshlrev_b32_e32 v108, 16, v66
	v_and_b32_e32 v109, 0xffff0000, v66
	v_pk_mul_f32 v[106:107], v[96:97], v[106:107] op_sel_hi:[0,1]
	v_pk_fma_f32 v[68:69], v[6:7], v[106:107], v[108:109]
	v_lshlrev_b32_e32 v106, 16, v75
	v_and_b32_e32 v107, 0xffff0000, v75
	v_lshlrev_b32_e32 v108, 16, v67
	v_and_b32_e32 v109, 0xffff0000, v67
	v_pk_mul_f32 v[106:107], v[96:97], v[106:107] op_sel_hi:[0,1]
	v_pk_fma_f32 v[70:71], v[8:9], v[106:107], v[108:109]
	global_store_dwordx4 v23, v[60:63], s[6:7] offset:2048
	global_store_dwordx4 v23, v[68:71], s[6:7] offset:2064
	v_add_u32_e32 v18, 0x400000, v18
	v_add_u32_e32 v20, 0x400000, v20
	v_add_u32_e32 v21, 0x2000, v21
	global_load_dwordx4 v[60:63], v18, s[4:5]
	global_load_dwordx4 v[68:71], v20, s[4:5]
	global_load_dwordx4 v[64:67], v18, s[4:5] offset:1024
	global_load_dwordx4 v[72:75], v20, s[4:5] offset:1024
	global_load_dword v76, v21, s[4:5]
	s_waitcnt vmcnt(27)
; __device__ __forceinline__ float bflo(unsigned w) { return __uint_as_float(w << 16); }
; __device__ __forceinline__ float bfhi(unsigned w) { return __uint_as_float(w & 0xffff0000u); }
; __device__ __forceinline__ void resid_rows(bf16_t* R, const bf16_t* Y, const float* ssqY, const float* g, float* rstd_out, float* outf, bool wf32, int row_lo, int row_hi, int yoff, int gw, int NGW, int lane) {
;     ...
;         for (int k = 0; k < RP; ++k) { const int row = row0 + k * NGW; const bool ok = row < row_hi; const int rw = ok ? row : row0;
;             ssv[k] = ssqY[rw];
; #pragma unroll
;             for (int j = 0; j < 2; ++j) { const int c = 8 * lane + 512 * j; rr[k][j] = *(const u32x4*)(R + (size_t)rw * DM + c); oo[k][j] = *(const u32x4*)(Y + (size_t)(rw - yoff) * DM + c); } }
; #pragma unroll
;         for (int k = 0; k < RP; ++k) { const int row = row0 + k * NGW; if (row < row_hi) {
;             const float rs = __builtin_amdgcn_rsqf(ssv[k] * (1.0f / DM) + RMS_EPS); float s = 0.f;
; #pragma unroll
;             for (int j = 0; j < 2; ++j) { const int c = 8 * lane + 512 * j; const u32x4 r = rr[k][j], o = oo[k][j]; const f32x4 ga = gv[j][0], gb = gv[j][1];
;                 f32x4 ya, yb; ya[0] = bflo(r.x) + bflo(o.x) * rs * ga[0]; ya[1] = bfhi(r.x) + bfhi(o.x) * rs * ga[1]; ya[2] = bflo(r.y) + bflo(o.y) * rs * ga[2]; ya[3] = bfhi(r.y) + bfhi(o.y) * rs * ga[3];
;                 yb[0] = bflo(r.z) + bflo(o.z) * rs * gb[0]; yb[1] = bfhi(r.z) + bfhi(o.z) * rs * gb[1]; yb[2] = bflo(r.w) + bflo(o.w) * rs * gb[2]; yb[3] = bfhi(r.w) + bfhi(o.w) * rs * gb[3];
;                 if (wf32) { *(f32x4*)(outf + (size_t)row * DM + c) = ya; *(f32x4*)(outf + (size_t)row * DM + c + 4) = yb; }
;                 s += (ya[0] * ya[0] + ya[1] * ya[1]) + (ya[2] * ya[2] + ya[3] * ya[3]) + (yb[0] * yb[0] + yb[1] * yb[1]) + (yb[2] * yb[2] + yb[3] * yb[3]);
;                 u32x4 w; w.x = pk2(ya[0], ya[1]); w.y = pk2(ya[2], ya[3]); w.z = pk2(yb[0], yb[1]); w.w = pk2(yb[2], yb[3]); *(u32x4*)(R + (size_t)row * DM + c) = w; }
	v_fmamk_f32 v96, v94, 0x3a800000, v244
	v_rsq_f32_e32 v96, v96
	v_add_u32_e32 v23, 0x800000, v23
	v_lshlrev_b32_e32 v106, 16, v86
	v_and_b32_e32 v107, 0xffff0000, v86
	v_lshlrev_b32_e32 v108, 16, v78
	v_and_b32_e32 v109, 0xffff0000, v78
	v_pk_mul_f32 v[106:107], v[96:97], v[106:107] op_sel_hi:[0,1]
	v_pk_fma_f32 v[98:99], v[10:11], v[106:107], v[108:109]
	v_lshlrev_b32_e32 v106, 16, v87
	v_and_b32_e32 v107, 0xffff0000, v87
	v_lshlrev_b32_e32 v108, 16, v79
	v_and_b32_e32 v109, 0xffff0000, v79
	v_pk_mul_f32 v[106:107], v[96:97], v[106:107] op_sel_hi:[0,1]
	v_pk_fma_f32 v[100:101], v[12:13], v[106:107], v[108:109]
	v_lshlrev_b32_e32 v106, 16, v88
	v_and_b32_e32 v107, 0xffff0000, v88
	v_lshlrev_b32_e32 v108, 16, v80
	v_and_b32_e32 v109, 0xffff0000, v80
	v_pk_mul_f32 v[106:107], v[96:97], v[106:107] op_sel_hi:[0,1]
	v_pk_fma_f32 v[102:103], v[14:15], v[106:107], v[108:109]
	v_lshlrev_b32_e32 v106, 16, v89
	v_and_b32_e32 v107, 0xffff0000, v89
	v_lshlrev_b32_e32 v108, 16, v81
	v_and_b32_e32 v109, 0xffff0000, v81
	v_pk_mul_f32 v[106:107], v[96:97], v[106:107] op_sel_hi:[0,1]
	v_pk_fma_f32 v[104:105], v[16:17], v[106:107], v[108:109]
	global_store_dwordx4 v23, v[98:101], s[6:7]
	global_store_dwordx4 v23, v[102:105], s[6:7] offset:16
	v_lshlrev_b32_e32 v106, 16, v90
	v_and_b32_e32 v107, 0xffff0000, v90
	v_lshlrev_b32_e32 v108, 16, v82
	v_and_b32_e32 v109, 0xffff0000, v82
	v_pk_mul_f32 v[106:107], v[96:97], v[106:107] op_sel_hi:[0,1]
	v_pk_fma_f32 v[78:79], v[2:3], v[106:107], v[108:109]
	v_lshlrev_b32_e32 v106, 16, v91
	v_and_b32_e32 v107, 0xffff0000, v91
	v_lshlrev_b32_e32 v108, 16, v83
	v_and_b32_e32 v109, 0xffff0000, v83
	v_pk_mul_f32 v[106:107], v[96:97], v[106:107] op_sel_hi:[0,1]
	v_pk_fma_f32 v[80:81], v[4:5], v[106:107], v[108:109]
	v_lshlrev_b32_e32 v106, 16, v92
	v_and_b32_e32 v107, 0xffff0000, v92
	v_lshlrev_b32_e32 v108, 16, v84
	v_and_b32_e32 v109, 0xffff0000, v84
	v_pk_mul_f32 v[106:107], v[96:97], v[106:107] op_sel_hi:[0,1]
	v_pk_fma_f32 v[86:87], v[6:7], v[106:107], v[108:109]
	v_lshlrev_b32_e32 v106, 16, v93
	v_and_b32_e32 v107, 0xffff0000, v93
	v_lshlrev_b32_e32 v108, 16, v85
	v_and_b32_e32 v109, 0xffff0000, v85
	v_pk_mul_f32 v[106:107], v[96:97], v[106:107] op_sel_hi:[0,1]
	v_pk_fma_f32 v[88:89], v[8:9], v[106:107], v[108:109]
	global_store_dwordx4 v23, v[78:81], s[6:7] offset:2048
	global_store_dwordx4 v23, v[86:89], s[6:7] offset:2064
	v_add_u32_e32 v18, 0x400000, v18
	v_add_u32_e32 v20, 0x400000, v20
	v_add_u32_e32 v21, 0x2000, v21
	global_load_dwordx4 v[78:81], v18, s[4:5]
	global_load_dwordx4 v[86:89], v20, s[4:5]
	global_load_dwordx4 v[82:85], v18, s[4:5] offset:1024
	global_load_dwordx4 v[90:93], v20, s[4:5] offset:1024
	global_load_dword v94, v21, s[4:5]
	s_waitcnt vmcnt(27)
	v_fmamk_f32 v96, v40, 0x3a800000, v244
	v_rsq_f32_e32 v96, v96
	v_add_u32_e32 v23, 0x800000, v23
	v_lshlrev_b32_e32 v106, 16, v32
	v_and_b32_e32 v107, 0xffff0000, v32
	v_lshlrev_b32_e32 v108, 16, v24
	v_and_b32_e32 v109, 0xffff0000, v24
	v_pk_mul_f32 v[106:107], v[96:97], v[106:107] op_sel_hi:[0,1]
	v_pk_fma_f32 v[98:99], v[10:11], v[106:107], v[108:109]
	v_lshlrev_b32_e32 v106, 16, v33
	v_and_b32_e32 v107, 0xffff0000, v33
	v_lshlrev_b32_e32 v108, 16, v25
	v_and_b32_e32 v109, 0xffff0000, v25
	v_pk_mul_f32 v[106:107], v[96:97], v[106:107] op_sel_hi:[0,1]
	v_pk_fma_f32 v[100:101], v[12:13], v[106:107], v[108:109]
	v_lshlrev_b32_e32 v106, 16, v34
	v_and_b32_e32 v107, 0xffff0000, v34
	v_lshlrev_b32_e32 v108, 16, v26
	v_and_b32_e32 v109, 0xffff0000, v26
	v_pk_mul_f32 v[106:107], v[96:97], v[106:107] op_sel_hi:[0,1]
	v_pk_fma_f32 v[102:103], v[14:15], v[106:107], v[108:109]
	v_lshlrev_b32_e32 v106, 16, v35
	v_and_b32_e32 v107, 0xffff0000, v35
	v_lshlrev_b32_e32 v108, 16, v27
	v_and_b32_e32 v109, 0xffff0000, v27
	v_pk_mul_f32 v[106:107], v[96:97], v[106:107] op_sel_hi:[0,1]
	v_pk_fma_f32 v[104:105], v[16:17], v[106:107], v[108:109]
	global_store_dwordx4 v23, v[98:101], s[6:7]
	global_store_dwordx4 v23, v[102:105], s[6:7] offset:16
	v_lshlrev_b32_e32 v106, 16, v36
	v_and_b32_e32 v107, 0xffff0000, v36
	v_lshlrev_b32_e32 v108, 16, v28
	v_and_b32_e32 v109, 0xffff0000, v28
	v_pk_mul_f32 v[106:107], v[96:97], v[106:107] op_sel_hi:[0,1]
	v_pk_fma_f32 v[24:25], v[2:3], v[106:107], v[108:109]
	v_lshlrev_b32_e32 v106, 16, v37
	v_and_b32_e32 v107, 0xffff0000, v37
	v_lshlrev_b32_e32 v108, 16, v29
	v_and_b32_e32 v109, 0xffff0000, v29
	v_pk_mul_f32 v[106:107], v[96:97], v[106:107] op_sel_hi:[0,1]
	v_pk_fma_f32 v[26:27], v[4:5], v[106:107], v[108:109]
	v_lshlrev_b32_e32 v106, 16, v38
	v_and_b32_e32 v107, 0xffff0000, v38
	v_lshlrev_b32_e32 v108, 16, v30
	v_and_b32_e32 v109, 0xffff0000, v30
	v_pk_mul_f32 v[106:107], v[96:97], v[106:107] op_sel_hi:[0,1]
	v_pk_fma_f32 v[32:33], v[6:7], v[106:107], v[108:109]
	v_lshlrev_b32_e32 v106, 16, v39
	v_and_b32_e32 v107, 0xffff0000, v39
	v_lshlrev_b32_e32 v108, 16, v31
	v_and_b32_e32 v109, 0xffff0000, v31
	v_pk_mul_f32 v[106:107], v[96:97], v[106:107] op_sel_hi:[0,1]
	v_pk_fma_f32 v[34:35], v[8:9], v[106:107], v[108:109]
	global_store_dwordx4 v23, v[24:27], s[6:7] offset:2048
	global_store_dwordx4 v23, v[32:35], s[6:7] offset:2064
	s_nop 1
	s_waitcnt vmcnt(22)
; __device__ __forceinline__ float bflo(unsigned w) { return __uint_as_float(w << 16); }
; __device__ __forceinline__ float bfhi(unsigned w) { return __uint_as_float(w & 0xffff0000u); }
; __device__ __forceinline__ void resid_rows(bf16_t* R, const bf16_t* Y, const float* ssqY, const float* g, float* rstd_out, float* outf, bool wf32, int row_lo, int row_hi, int yoff, int gw, int NGW, int lane) {
;     ...
;         for (int k = 0; k < RP; ++k) { const int row = row0 + k * NGW; const bool ok = row < row_hi; const int rw = ok ? row : row0;
;             ssv[k] = ssqY[rw];
; #pragma unroll
;             for (int j = 0; j < 2; ++j) { const int c = 8 * lane + 512 * j; rr[k][j] = *(const u32x4*)(R + (size_t)rw * DM + c); oo[k][j] = *(const u32x4*)(Y + (size_t)(rw - yoff) * DM + c); } }
; #pragma unroll
;         for (int k = 0; k < RP; ++k) { const int row = row0 + k * NGW; if (row < row_hi) {
;             const float rs = __builtin_amdgcn_rsqf(ssv[k] * (1.0f / DM) + RMS_EPS); float s = 0.f;
; #pragma unroll
;             for (int j = 0; j < 2; ++j) { const int c = 8 * lane + 512 * j; const u32x4 r = rr[k][j], o = oo[k][j]; const f32x4 ga = gv[j][0], gb = gv[j][1];
;                 f32x4 ya, yb; ya[0] = bflo(r.x) + bflo(o.x) * rs * ga[0]; ya[1] = bfhi(r.x) + bfhi(o.x) * rs * ga[1]; ya[2] = bflo(r.y) + bflo(o.y) * rs * ga[2]; ya[3] = bfhi(r.y) + bfhi(o.y) * rs * ga[3];
;                 yb[0] = bflo(r.z) + bflo(o.z) * rs * gb[0]; yb[1] = bfhi(r.z) + bfhi(o.z) * rs * gb[1]; yb[2] = bflo(r.w) + bflo(o.w) * rs * gb[2]; yb[3] = bfhi(r.w) + bfhi(o.w) * rs * gb[3];
;                 if (wf32) { *(f32x4*)(outf + (size_t)row * DM + c) = ya; *(f32x4*)(outf + (size_t)row * DM + c + 4) = yb; }
;                 s += (ya[0] * ya[0] + ya[1] * ya[1]) + (ya[2] * ya[2] + ya[3] * ya[3]) + (yb[0] * yb[0] + yb[1] * yb[1]) + (yb[2] * yb[2] + yb[3] * yb[3]);
;                 u32x4 w; w.x = pk2(ya[0], ya[1]); w.y = pk2(ya[2], ya[3]); w.z = pk2(yb[0], yb[1]); w.w = pk2(yb[2], yb[3]); *(u32x4*)(R + (size_t)row * DM + c) = w; }
	v_fmamk_f32 v96, v58, 0x3a800000, v244
	v_rsq_f32_e32 v96, v96
	v_add_u32_e32 v23, 0x800000, v23
	v_lshlrev_b32_e32 v106, 16, v50
	v_and_b32_e32 v107, 0xffff0000, v50
	v_lshlrev_b32_e32 v108, 16, v42
	v_and_b32_e32 v109, 0xffff0000, v42
	v_pk_mul_f32 v[106:107], v[96:97], v[106:107] op_sel_hi:[0,1]
	v_pk_fma_f32 v[98:99], v[10:11], v[106:107], v[108:109]
	v_lshlrev_b32_e32 v106, 16, v51
	v_and_b32_e32 v107, 0xffff0000, v51
	v_lshlrev_b32_e32 v108, 16, v43
	v_and_b32_e32 v109, 0xffff0000, v43
	v_pk_mul_f32 v[106:107], v[96:97], v[106:107] op_sel_hi:[0,1]
	v_pk_fma_f32 v[100:101], v[12:13], v[106:107], v[108:109]
	v_lshlrev_b32_e32 v106, 16, v52
	v_and_b32_e32 v107, 0xffff0000, v52
	v_lshlrev_b32_e32 v108, 16, v44
	v_and_b32_e32 v109, 0xffff0000, v44
	v_pk_mul_f32 v[106:107], v[96:97], v[106:107] op_sel_hi:[0,1]
	v_pk_fma_f32 v[102:103], v[14:15], v[106:107], v[108:109]
	v_lshlrev_b32_e32 v106, 16, v53
	v_and_b32_e32 v107, 0xffff0000, v53
	v_lshlrev_b32_e32 v108, 16, v45
	v_and_b32_e32 v109, 0xffff0000, v45
	v_pk_mul_f32 v[106:107], v[96:97], v[106:107] op_sel_hi:[0,1]
	v_pk_fma_f32 v[104:105], v[16:17], v[106:107], v[108:109]
	global_store_dwordx4 v23, v[98:101], s[6:7]
	global_store_dwordx4 v23, v[102:105], s[6:7] offset:16
	v_lshlrev_b32_e32 v106, 16, v54
	v_and_b32_e32 v107, 0xffff0000, v54
	v_lshlrev_b32_e32 v108, 16, v46
	v_and_b32_e32 v109, 0xffff0000, v46
	v_pk_mul_f32 v[106:107], v[96:97], v[106:107] op_sel_hi:[0,1]
	v_pk_fma_f32 v[42:43], v[2:3], v[106:107], v[108:109]
	v_lshlrev_b32_e32 v106, 16, v55
	v_and_b32_e32 v107, 0xffff0000, v55
	v_lshlrev_b32_e32 v108, 16, v47
	v_and_b32_e32 v109, 0xffff0000, v47
	v_pk_mul_f32 v[106:107], v[96:97], v[106:107] op_sel_hi:[0,1]
	v_pk_fma_f32 v[44:45], v[4:5], v[106:107], v[108:109]
	v_lshlrev_b32_e32 v106, 16, v56
	v_and_b32_e32 v107, 0xffff0000, v56
	v_lshlrev_b32_e32 v108, 16, v48
	v_and_b32_e32 v109, 0xffff0000, v48
	v_pk_mul_f32 v[106:107], v[96:97], v[106:107] op_sel_hi:[0,1]
	v_pk_fma_f32 v[50:51], v[6:7], v[106:107], v[108:109]
	v_lshlrev_b32_e32 v106, 16, v57
	v_and_b32_e32 v107, 0xffff0000, v57
	v_lshlrev_b32_e32 v108, 16, v49
	v_and_b32_e32 v109, 0xffff0000, v49
	v_pk_mul_f32 v[106:107], v[96:97], v[106:107] op_sel_hi:[0,1]
	v_pk_fma_f32 v[52:53], v[8:9], v[106:107], v[108:109]
	global_store_dwordx4 v23, v[42:45], s[6:7] offset:2048
	global_store_dwordx4 v23, v[50:53], s[6:7] offset:2064
	s_nop 1
	s_waitcnt vmcnt(17)
; __device__ __forceinline__ float bflo(unsigned w) { return __uint_as_float(w << 16); }
; __device__ __forceinline__ float bfhi(unsigned w) { return __uint_as_float(w & 0xffff0000u); }
; __device__ __forceinline__ void resid_rows(bf16_t* R, const bf16_t* Y, const float* ssqY, const float* g, float* rstd_out, float* outf, bool wf32, int row_lo, int row_hi, int yoff, int gw, int NGW, int lane) {
;     ...
;         for (int k = 0; k < RP; ++k) { const int row = row0 + k * NGW; const bool ok = row < row_hi; const int rw = ok ? row : row0;
;             ssv[k] = ssqY[rw];
; #pragma unroll
;             for (int j = 0; j < 2; ++j) { const int c = 8 * lane + 512 * j; rr[k][j] = *(const u32x4*)(R + (size_t)rw * DM + c); oo[k][j] = *(const u32x4*)(Y + (size_t)(rw - yoff) * DM + c); } }
; #pragma unroll
;         for (int k = 0; k < RP; ++k) { const int row = row0 + k * NGW; if (row < row_hi) {
;             const float rs = __builtin_amdgcn_rsqf(ssv[k] * (1.0f / DM) + RMS_EPS); float s = 0.f;
; #pragma unroll
;             for (int j = 0; j < 2; ++j) { const int c = 8 * lane + 512 * j; const u32x4 r = rr[k][j], o = oo[k][j]; const f32x4 ga = gv[j][0], gb = gv[j][1];
;                 f32x4 ya, yb; ya[0] = bflo(r.x) + bflo(o.x) * rs * ga[0]; ya[1] = bfhi(r.x) + bfhi(o.x) * rs * ga[1]; ya[2] = bflo(r.y) + bflo(o.y) * rs * ga[2]; ya[3] = bfhi(r.y) + bfhi(o.y) * rs * ga[3];
;                 yb[0] = bflo(r.z) + bflo(o.z) * rs * gb[0]; yb[1] = bfhi(r.z) + bfhi(o.z) * rs * gb[1]; yb[2] = bflo(r.w) + bflo(o.w) * rs * gb[2]; yb[3] = bfhi(r.w) + bfhi(o.w) * rs * gb[3];
;                 if (wf32) { *(f32x4*)(outf + (size_t)row * DM + c) = ya; *(f32x4*)(outf + (size_t)row * DM + c + 4) = yb; }
;                 s += (ya[0] * ya[0] + ya[1] * ya[1]) + (ya[2] * ya[2] + ya[3] * ya[3]) + (yb[0] * yb[0] + yb[1] * yb[1]) + (yb[2] * yb[2] + yb[3] * yb[3]);
;                 u32x4 w; w.x = pk2(ya[0], ya[1]); w.y = pk2(ya[2], ya[3]); w.z = pk2(yb[0], yb[1]); w.w = pk2(yb[2], yb[3]); *(u32x4*)(R + (size_t)row * DM + c) = w; }
	v_fmamk_f32 v96, v76, 0x3a800000, v244
	v_rsq_f32_e32 v96, v96
	v_add_u32_e32 v23, 0x800000, v23
	v_lshlrev_b32_e32 v106, 16, v68
	v_and_b32_e32 v107, 0xffff0000, v68
	v_lshlrev_b32_e32 v108, 16, v60
	v_and_b32_e32 v109, 0xffff0000, v60
	v_pk_mul_f32 v[106:107], v[96:97], v[106:107] op_sel_hi:[0,1]
	v_pk_fma_f32 v[98:99], v[10:11], v[106:107], v[108:109]
	v_lshlrev_b32_e32 v106, 16, v69
	v_and_b32_e32 v107, 0xffff0000, v69
	v_lshlrev_b32_e32 v108, 16, v61
	v_and_b32_e32 v109, 0xffff0000, v61
	v_pk_mul_f32 v[106:107], v[96:97], v[106:107] op_sel_hi:[0,1]
	v_pk_fma_f32 v[100:101], v[12:13], v[106:107], v[108:109]
	v_lshlrev_b32_e32 v106, 16, v70
	v_and_b32_e32 v107, 0xffff0000, v70
	v_lshlrev_b32_e32 v108, 16, v62
	v_and_b32_e32 v109, 0xffff0000, v62
	v_pk_mul_f32 v[106:107], v[96:97], v[106:107] op_sel_hi:[0,1]
	v_pk_fma_f32 v[102:103], v[14:15], v[106:107], v[108:109]
	v_lshlrev_b32_e32 v106, 16, v71
	v_and_b32_e32 v107, 0xffff0000, v71
	v_lshlrev_b32_e32 v108, 16, v63
	v_and_b32_e32 v109, 0xffff0000, v63
	v_pk_mul_f32 v[106:107], v[96:97], v[106:107] op_sel_hi:[0,1]
	v_pk_fma_f32 v[104:105], v[16:17], v[106:107], v[108:109]
	global_store_dwordx4 v23, v[98:101], s[6:7]
	global_store_dwordx4 v23, v[102:105], s[6:7] offset:16
	v_lshlrev_b32_e32 v106, 16, v72
	v_and_b32_e32 v107, 0xffff0000, v72
	v_lshlrev_b32_e32 v108, 16, v64
	v_and_b32_e32 v109, 0xffff0000, v64
	v_pk_mul_f32 v[106:107], v[96:97], v[106:107] op_sel_hi:[0,1]
	v_pk_fma_f32 v[60:61], v[2:3], v[106:107], v[108:109]
	v_lshlrev_b32_e32 v106, 16, v73
	v_and_b32_e32 v107, 0xffff0000, v73
	v_lshlrev_b32_e32 v108, 16, v65
	v_and_b32_e32 v109, 0xffff0000, v65
	v_pk_mul_f32 v[106:107], v[96:97], v[106:107] op_sel_hi:[0,1]
	v_pk_fma_f32 v[62:63], v[4:5], v[106:107], v[108:109]
	v_lshlrev_b32_e32 v106, 16, v74
	v_and_b32_e32 v107, 0xffff0000, v74
	v_lshlrev_b32_e32 v108, 16, v66
	v_and_b32_e32 v109, 0xffff0000, v66
	v_pk_mul_f32 v[106:107], v[96:97], v[106:107] op_sel_hi:[0,1]
	v_pk_fma_f32 v[68:69], v[6:7], v[106:107], v[108:109]
	v_lshlrev_b32_e32 v106, 16, v75
	v_and_b32_e32 v107, 0xffff0000, v75
	v_lshlrev_b32_e32 v108, 16, v67
	v_and_b32_e32 v109, 0xffff0000, v67
	v_pk_mul_f32 v[106:107], v[96:97], v[106:107] op_sel_hi:[0,1]
	v_pk_fma_f32 v[70:71], v[8:9], v[106:107], v[108:109]
	global_store_dwordx4 v23, v[60:63], s[6:7] offset:2048
	global_store_dwordx4 v23, v[68:71], s[6:7] offset:2064
	s_nop 1
	s_waitcnt vmcnt(12)
	v_fmamk_f32 v96, v94, 0x3a800000, v244
	v_rsq_f32_e32 v96, v96
	v_add_u32_e32 v23, 0x800000, v23
	v_lshlrev_b32_e32 v106, 16, v86
	v_and_b32_e32 v107, 0xffff0000, v86
	v_lshlrev_b32_e32 v108, 16, v78
	v_and_b32_e32 v109, 0xffff0000, v78
	v_pk_mul_f32 v[106:107], v[96:97], v[106:107] op_sel_hi:[0,1]
	v_pk_fma_f32 v[98:99], v[10:11], v[106:107], v[108:109]
	v_lshlrev_b32_e32 v106, 16, v87
	v_and_b32_e32 v107, 0xffff0000, v87
	v_lshlrev_b32_e32 v108, 16, v79
	v_and_b32_e32 v109, 0xffff0000, v79
	v_pk_mul_f32 v[106:107], v[96:97], v[106:107] op_sel_hi:[0,1]
	v_pk_fma_f32 v[100:101], v[12:13], v[106:107], v[108:109]
	v_lshlrev_b32_e32 v106, 16, v88
	v_and_b32_e32 v107, 0xffff0000, v88
	v_lshlrev_b32_e32 v108, 16, v80
	v_and_b32_e32 v109, 0xffff0000, v80
	v_pk_mul_f32 v[106:107], v[96:97], v[106:107] op_sel_hi:[0,1]
	v_pk_fma_f32 v[102:103], v[14:15], v[106:107], v[108:109]
	v_lshlrev_b32_e32 v106, 16, v89
	v_and_b32_e32 v107, 0xffff0000, v89
	v_lshlrev_b32_e32 v108, 16, v81
	v_and_b32_e32 v109, 0xffff0000, v81
	v_pk_mul_f32 v[106:107], v[96:97], v[106:107] op_sel_hi:[0,1]
	v_pk_fma_f32 v[104:105], v[16:17], v[106:107], v[108:109]
	global_store_dwordx4 v23, v[98:101], s[6:7]
	global_store_dwordx4 v23, v[102:105], s[6:7] offset:16
	v_lshlrev_b32_e32 v106, 16, v90
	v_and_b32_e32 v107, 0xffff0000, v90
	v_lshlrev_b32_e32 v108, 16, v82
	v_and_b32_e32 v109, 0xffff0000, v82
	v_pk_mul_f32 v[106:107], v[96:97], v[106:107] op_sel_hi:[0,1]
	v_pk_fma_f32 v[78:79], v[2:3], v[106:107], v[108:109]
	v_lshlrev_b32_e32 v106, 16, v91
	v_and_b32_e32 v107, 0xffff0000, v91
	v_lshlrev_b32_e32 v108, 16, v83
	v_and_b32_e32 v109, 0xffff0000, v83
	v_pk_mul_f32 v[106:107], v[96:97], v[106:107] op_sel_hi:[0,1]
	v_pk_fma_f32 v[80:81], v[4:5], v[106:107], v[108:109]
	v_lshlrev_b32_e32 v106, 16, v92
	v_and_b32_e32 v107, 0xffff0000, v92
	v_lshlrev_b32_e32 v108, 16, v84
	v_and_b32_e32 v109, 0xffff0000, v84
	v_pk_mul_f32 v[106:107], v[96:97], v[106:107] op_sel_hi:[0,1]
	v_pk_fma_f32 v[86:87], v[6:7], v[106:107], v[108:109]
	v_lshlrev_b32_e32 v106, 16, v93
	v_and_b32_e32 v107, 0xffff0000, v93
	v_lshlrev_b32_e32 v108, 16, v85
	v_and_b32_e32 v109, 0xffff0000, v85
	v_pk_mul_f32 v[106:107], v[96:97], v[106:107] op_sel_hi:[0,1]
	v_pk_fma_f32 v[88:89], v[8:9], v[106:107], v[108:109]
	global_store_dwordx4 v23, v[78:81], s[6:7] offset:2048
	global_store_dwordx4 v23, v[86:89], s[6:7] offset:2064
	s_branch .LBB0_907
